# prep DFT-matrix generation: cos table lookups in LDS (bank-conflicted) replaced by v_cos_f32 of m/2048 revolutions, on top of adaLN 64-loads-in-flight
# speedup vs baseline: 1.0044x; 1.0044x over previous
; __device__ __forceinline__ unsigned cvt_pk_bf16(float lo, float hi) { unsigned r; asm("v_cvt_pk_bf16_f32 %0, %1, %2" : "=v"(r) : "v"(lo), "v"(hi)); return r; }
; __device__ __forceinline__ void prep_phase(const Params& p, LAS unsigned char* lds) {
;     ...
;         for (int e = gt; e < 2048 * 4096 / 8; e += NGT) {
;             const int k = e >> 9, col0 = (e & 511) * 8, s = col0 >> 11; float v[8];
; #pragma unroll
;             for (int j = 0; j < 8; ++j) { const int n = (col0 + j) & 2047, m = (k * n) & 2047; v[j] = s ? -tab[(m - 512) & 2047] * nl : tab[m] * nl; }
;             u32x4 o; o.x = cvt_pk_bf16(v[0], v[1]); o.y = cvt_pk_bf16(v[2], v[3]); o.z = cvt_pk_bf16(v[4], v[5]); o.w = cvt_pk_bf16(v[6], v[7]);
;             *(u32x4*)((bf16_t*)(ws + WS_DFTL) + (size_t)e * 8) = o;
;         }
.LBB0_92:
	v_lshrrev_b32_e32 v8, 9, v7
	v_and_b32_e32 v9, 0x100, v7
	v_add_u32_e32 v7, s0, v7
	v_mul_lo_u32 v10, v4, v8
	v_cmp_lt_i32_e32 vcc, s10, v7
	s_or_b64 s[8:9], vcc, s[8:9]
	v_cmp_eq_u32_e32 vcc, 0, v9
	v_cndmask_b32_e32 v11, v5, v6, vcc
	v_mov_b32_e32 v9, 0x600
	v_cndmask_b32_e64 v9, v9, 0, vcc
	v_add_u32_e32 v10, v10, v9
	v_add_u32_e32 v12, v10, v8
	v_add_u32_e32 v13, v12, v8
	v_add_u32_e32 v14, v13, v8
	v_add_u32_e32 v15, v14, v8
	v_add_u32_e32 v16, v15, v8
	v_add_u32_e32 v17, v16, v8
	v_add_u32_e32 v18, v17, v8
	v_and_b32_e32 v10, 0x7ff, v10
	v_and_b32_e32 v12, 0x7ff, v12
	v_and_b32_e32 v13, 0x7ff, v13
	v_and_b32_e32 v14, 0x7ff, v14
	v_and_b32_e32 v15, 0x7ff, v15
	v_and_b32_e32 v16, 0x7ff, v16
	v_and_b32_e32 v17, 0x7ff, v17
	v_and_b32_e32 v18, 0x7ff, v18
	v_cvt_f32_u32_e32 v10, v10
	v_cvt_f32_u32_e32 v12, v12
	v_cvt_f32_u32_e32 v13, v13
	v_cvt_f32_u32_e32 v14, v14
	v_cvt_f32_u32_e32 v15, v15
	v_cvt_f32_u32_e32 v16, v16
	v_cvt_f32_u32_e32 v17, v17
	v_cvt_f32_u32_e32 v18, v18
	v_mul_f32_e32 v10, 0x3a000000, v10
	v_mul_f32_e32 v12, 0x3a000000, v12
	v_mul_f32_e32 v13, 0x3a000000, v13
	v_mul_f32_e32 v14, 0x3a000000, v14
	v_mul_f32_e32 v15, 0x3a000000, v15
	v_mul_f32_e32 v16, 0x3a000000, v16
	v_mul_f32_e32 v17, 0x3a000000, v17
	v_mul_f32_e32 v18, 0x3a000000, v18
	v_cos_f32_e32 v10, v10
	v_cos_f32_e32 v12, v12
	v_cos_f32_e32 v13, v13
	v_cos_f32_e32 v14, v14
	v_cos_f32_e32 v15, v15
	v_cos_f32_e32 v16, v16
	v_cos_f32_e32 v17, v17
	v_cos_f32_e32 v18, v18
	v_add_u32_e32 v4, s1, v4
	s_nop 0
	v_mul_f32_e32 v10, v10, v11
	v_mul_f32_e32 v12, v12, v11
	v_mul_f32_e32 v13, v13, v11
	v_mul_f32_e32 v14, v14, v11
	v_mul_f32_e32 v15, v15, v11
	v_mul_f32_e32 v16, v16, v11
	v_mul_f32_e32 v17, v17, v11
	v_mul_f32_e32 v18, v18, v11
	v_cvt_pk_bf16_f32 v20, v10, v12
	v_cvt_pk_bf16_f32 v21, v13, v14
	v_cvt_pk_bf16_f32 v22, v15, v16
	v_cvt_pk_bf16_f32 v23, v17, v18
	global_store_dwordx4 v[2:3], v[20:23], off
	v_lshl_add_u64 v[2:3], v[2:3], 0, s[6:7]
	s_andn2_b64 exec, exec, s[8:9]
	s_cbranch_execnz .LBB0_92
